# attention fast path v2b: PV gap fillers rebalanced (sums and last cvt group moved to PV MFMAs 9-12, LDS writes to 13-16)
# speedup vs baseline: 1.0031x; 1.0031x over previous
.LaF1_2:
	v_sub_f32_e32 v66, v66, v183
	v_sub_f32_e32 v67, v67, v183
	v_sub_f32_e32 v68, v68, v183
	v_sub_f32_e32 v69, v69, v183
	v_sub_f32_e32 v70, v70, v183
	v_sub_f32_e32 v71, v71, v183
	v_sub_f32_e32 v72, v72, v183
	v_sub_f32_e32 v73, v73, v183
	v_sub_f32_e32 v74, v74, v183
	v_sub_f32_e32 v75, v75, v183
	v_sub_f32_e32 v76, v76, v183
	v_sub_f32_e32 v77, v77, v183
	v_sub_f32_e32 v78, v78, v183
	v_sub_f32_e32 v79, v79, v183
	v_sub_f32_e32 v80, v80, v183
	v_sub_f32_e32 v81, v81, v183
	v_exp_f32_e32 v66, v66
	v_exp_f32_e32 v67, v67
	v_exp_f32_e32 v68, v68
	v_exp_f32_e32 v69, v69
	v_exp_f32_e32 v70, v70
	v_exp_f32_e32 v71, v71
	v_exp_f32_e32 v72, v72
	v_exp_f32_e32 v73, v73
	v_exp_f32_e32 v74, v74
	v_exp_f32_e32 v75, v75
	v_exp_f32_e32 v76, v76
	v_exp_f32_e32 v77, v77
	v_exp_f32_e32 v78, v78
	v_exp_f32_e32 v79, v79
	v_exp_f32_e32 v80, v80
	v_exp_f32_e32 v81, v81
	v_pk_add_f32 v[184:185], v[66:67], v[68:69]
	v_pk_add_f32 v[186:187], v[70:71], v[72:73]
	v_pk_add_f32 v[184:185], v[184:185], v[74:75]
	v_pk_add_f32 v[186:187], v[186:187], v[76:77]
	v_pk_add_f32 v[184:185], v[184:185], v[78:79]
	v_pk_add_f32 v[186:187], v[186:187], v[80:81]
	v_cvt_pk_bf16_f32 v66, v66, v67
	v_cvt_pk_bf16_f32 v67, v68, v69
	v_cvt_pk_bf16_f32 v68, v70, v71
	v_cvt_pk_bf16_f32 v69, v72, v73
	v_cvt_pk_bf16_f32 v70, v74, v75
	v_cvt_pk_bf16_f32 v71, v76, v77
	v_cvt_pk_bf16_f32 v72, v78, v79
	v_cvt_pk_bf16_f32 v73, v80, v81
	s_nop 1
	s_setprio 1
	s_waitcnt lgkmcnt(5)
	v_mfma_f32_32x32x16_bf16 v[50:65], v[196:199], v[66:69], v[50:65]
	ds_read_b128 v[220:223], v252 offset:34848
	v_sub_f32_e32 v82, v82, v183
	v_sub_f32_e32 v83, v83, v183
	v_sub_f32_e32 v84, v84, v183
	v_sub_f32_e32 v85, v85, v183
	v_sub_f32_e32 v86, v86, v183
	s_waitcnt lgkmcnt(5)
	v_mfma_f32_32x32x16_bf16 v[34:49], v[200:203], v[66:69], v[34:49]
	ds_read_b128 v[224:227], v252 offset:39456
	v_sub_f32_e32 v87, v87, v183
	v_sub_f32_e32 v88, v88, v183
	v_sub_f32_e32 v89, v89, v183
	v_sub_f32_e32 v90, v90, v183
	v_sub_f32_e32 v91, v91, v183
	s_waitcnt lgkmcnt(5)
	v_mfma_f32_32x32x16_bf16 v[18:33], v[204:207], v[66:69], v[18:33]
	ds_read_b128 v[228:231], v252 offset:25664
	v_sub_f32_e32 v92, v92, v183
	v_sub_f32_e32 v93, v93, v183
	v_sub_f32_e32 v94, v94, v183
	v_sub_f32_e32 v95, v95, v183
	v_sub_f32_e32 v96, v96, v183
	s_waitcnt lgkmcnt(5)
	v_mfma_f32_32x32x16_bf16 v[2:17], v[208:211], v[66:69], v[2:17]
	ds_read_b128 v[232:235], v252 offset:30272
	v_sub_f32_e32 v97, v97, v183
	v_exp_f32_e32 v82, v82
	v_exp_f32_e32 v83, v83
	v_exp_f32_e32 v84, v84
	v_exp_f32_e32 v85, v85
	s_waitcnt lgkmcnt(5)
	v_mfma_f32_32x32x16_bf16 v[50:65], v[212:215], v[70:73], v[50:65]
	ds_read_b128 v[236:239], v252 offset:34880
	v_exp_f32_e32 v86, v86
	v_exp_f32_e32 v87, v87
	v_exp_f32_e32 v88, v88
	v_exp_f32_e32 v89, v89
	v_exp_f32_e32 v90, v90
	s_waitcnt lgkmcnt(5)
	v_mfma_f32_32x32x16_bf16 v[34:49], v[216:219], v[70:73], v[34:49]
	ds_read_b128 v[240:243], v252 offset:39488
	v_exp_f32_e32 v91, v91
	v_exp_f32_e32 v92, v92
	v_exp_f32_e32 v93, v93
	v_exp_f32_e32 v94, v94
	v_exp_f32_e32 v95, v95
	s_waitcnt lgkmcnt(5)
	v_mfma_f32_32x32x16_bf16 v[18:33], v[220:223], v[70:73], v[18:33]
	ds_read_b128 v[196:199], v252 offset:25696
	v_exp_f32_e32 v96, v96
	v_exp_f32_e32 v97, v97
	v_cvt_pk_bf16_f32 v74, v82, v83
	v_cvt_pk_bf16_f32 v75, v84, v85
	v_cvt_pk_bf16_f32 v76, v86, v87
	s_waitcnt lgkmcnt(5)
	v_mfma_f32_32x32x16_bf16 v[2:17], v[224:227], v[70:73], v[2:17]
	ds_read_b128 v[200:203], v252 offset:30304
	v_cvt_pk_bf16_f32 v77, v88, v89
	s_waitcnt lgkmcnt(5)
	v_mfma_f32_32x32x16_bf16 v[50:65], v[228:231], v[74:77], v[50:65]
	ds_read_b128 v[204:207], v252 offset:34912
	v_cvt_pk_bf16_f32 v78, v90, v91
	v_cvt_pk_bf16_f32 v79, v92, v93
	v_cvt_pk_bf16_f32 v80, v94, v95
	v_cvt_pk_bf16_f32 v81, v96, v97
	s_waitcnt lgkmcnt(5)
	v_mfma_f32_32x32x16_bf16 v[34:49], v[232:235], v[74:77], v[34:49]
	ds_read_b128 v[208:211], v252 offset:39520
	v_pk_add_f32 v[184:185], v[184:185], v[82:83]
	v_pk_add_f32 v[186:187], v[186:187], v[84:85]
	v_pk_add_f32 v[184:185], v[184:185], v[86:87]
	v_pk_add_f32 v[186:187], v[186:187], v[88:89]
	s_waitcnt lgkmcnt(5)
	v_mfma_f32_32x32x16_bf16 v[18:33], v[236:239], v[74:77], v[18:33]
	v_pk_add_f32 v[184:185], v[184:185], v[90:91]
	v_pk_add_f32 v[186:187], v[186:187], v[92:93]
	v_pk_add_f32 v[184:185], v[184:185], v[94:95]
	v_pk_add_f32 v[186:187], v[186:187], v[96:97]
	s_waitcnt lgkmcnt(4)
	v_mfma_f32_32x32x16_bf16 v[2:17], v[240:243], v[74:77], v[2:17]
	v_pk_add_f32 v[184:185], v[184:185], v[186:187]
	v_add_f32_e32 v184, v184, v185
	v_add_f32_e32 v182, v182, v184
	s_waitcnt lgkmcnt(3)
	v_mfma_f32_32x32x16_bf16 v[50:65], v[196:199], v[78:81], v[50:65]
	s_bitcmp1_b32 s51, 0
	s_cselect_b32 s99, 0xac00, 0
	s_add_i32 s99, s99, 0
	v_add_u32_e32 v250, s99, v170
	s_waitcnt lgkmcnt(2)
	v_mfma_f32_32x32x16_bf16 v[34:49], v[200:203], v[78:81], v[34:49]
	s_waitcnt vmcnt(4)
	ds_write_b128 v250, v[98:101]
	s_waitcnt vmcnt(3)
	ds_write_b128 v250, v[102:105] offset:12800
	s_waitcnt lgkmcnt(3)
	v_mfma_f32_32x32x16_bf16 v[18:33], v[204:207], v[78:81], v[18:33]
	v_add_u32_e32 v250, s99, v172
	s_waitcnt vmcnt(2)
	ds_write_b128 v250, v[106:109] offset:256
	v_add_u32_e32 v250, s99, v169
	s_waitcnt lgkmcnt(3)
	v_mfma_f32_32x32x16_bf16 v[2:17], v[208:211], v[78:81], v[2:17]
	s_waitcnt vmcnt(1)
	ds_write_b128 v250, v[114:117] offset:25600
	s_waitcnt vmcnt(0)
	ds_write_b128 v250, v[146:149] offset:34816
	s_setprio 0
	s_branch .LBB0_1478

.LaF2_2:
	v_sub_f32_e32 v66, v66, v183
	v_sub_f32_e32 v67, v67, v183
	v_sub_f32_e32 v68, v68, v183
	v_sub_f32_e32 v69, v69, v183
	v_sub_f32_e32 v70, v70, v183
	v_sub_f32_e32 v71, v71, v183
	v_sub_f32_e32 v72, v72, v183
	v_sub_f32_e32 v73, v73, v183
	v_sub_f32_e32 v74, v74, v183
	v_sub_f32_e32 v75, v75, v183
	v_sub_f32_e32 v76, v76, v183
	v_sub_f32_e32 v77, v77, v183
	v_sub_f32_e32 v78, v78, v183
	v_sub_f32_e32 v79, v79, v183
	v_sub_f32_e32 v80, v80, v183
	v_sub_f32_e32 v81, v81, v183
	v_exp_f32_e32 v66, v66
	v_exp_f32_e32 v67, v67
	v_exp_f32_e32 v68, v68
	v_exp_f32_e32 v69, v69
	v_exp_f32_e32 v70, v70
	v_exp_f32_e32 v71, v71
	v_exp_f32_e32 v72, v72
	v_exp_f32_e32 v73, v73
	v_exp_f32_e32 v74, v74
	v_exp_f32_e32 v75, v75
	v_exp_f32_e32 v76, v76
	v_exp_f32_e32 v77, v77
	v_exp_f32_e32 v78, v78
	v_exp_f32_e32 v79, v79
	v_exp_f32_e32 v80, v80
	v_exp_f32_e32 v81, v81
	v_pk_add_f32 v[184:185], v[66:67], v[68:69]
	v_pk_add_f32 v[186:187], v[70:71], v[72:73]
	v_pk_add_f32 v[184:185], v[184:185], v[74:75]
	v_pk_add_f32 v[186:187], v[186:187], v[76:77]
	v_pk_add_f32 v[184:185], v[184:185], v[78:79]
	v_pk_add_f32 v[186:187], v[186:187], v[80:81]
	v_cvt_pk_bf16_f32 v66, v66, v67
	v_cvt_pk_bf16_f32 v67, v68, v69
	v_cvt_pk_bf16_f32 v68, v70, v71
	v_cvt_pk_bf16_f32 v69, v72, v73
	v_cvt_pk_bf16_f32 v70, v74, v75
	v_cvt_pk_bf16_f32 v71, v76, v77
	v_cvt_pk_bf16_f32 v72, v78, v79
	v_cvt_pk_bf16_f32 v73, v80, v81
	s_nop 1
	s_setprio 1
	s_waitcnt lgkmcnt(5)
	v_mfma_f32_32x32x16_bf16 v[50:65], v[196:199], v[66:69], v[50:65]
	ds_read_b128 v[220:223], v252 offset:34848
	v_sub_f32_e32 v82, v82, v183
	v_sub_f32_e32 v83, v83, v183
	v_sub_f32_e32 v84, v84, v183
	v_sub_f32_e32 v85, v85, v183
	v_sub_f32_e32 v86, v86, v183
	s_waitcnt lgkmcnt(5)
	v_mfma_f32_32x32x16_bf16 v[34:49], v[200:203], v[66:69], v[34:49]
	ds_read_b128 v[224:227], v252 offset:39456
	v_sub_f32_e32 v87, v87, v183
	v_sub_f32_e32 v88, v88, v183
	v_sub_f32_e32 v89, v89, v183
	v_sub_f32_e32 v90, v90, v183
	v_sub_f32_e32 v91, v91, v183
	s_waitcnt lgkmcnt(5)
	v_mfma_f32_32x32x16_bf16 v[18:33], v[204:207], v[66:69], v[18:33]
	ds_read_b128 v[228:231], v252 offset:25664
	v_sub_f32_e32 v92, v92, v183
	v_sub_f32_e32 v93, v93, v183
	v_sub_f32_e32 v94, v94, v183
	v_sub_f32_e32 v95, v95, v183
	v_sub_f32_e32 v96, v96, v183
	s_waitcnt lgkmcnt(5)
	v_mfma_f32_32x32x16_bf16 v[2:17], v[208:211], v[66:69], v[2:17]
	ds_read_b128 v[232:235], v252 offset:30272
	v_sub_f32_e32 v97, v97, v183
	v_exp_f32_e32 v82, v82
	v_exp_f32_e32 v83, v83
	v_exp_f32_e32 v84, v84
	v_exp_f32_e32 v85, v85
	s_waitcnt lgkmcnt(5)
	v_mfma_f32_32x32x16_bf16 v[50:65], v[212:215], v[70:73], v[50:65]
	ds_read_b128 v[236:239], v252 offset:34880
	v_exp_f32_e32 v86, v86
	v_exp_f32_e32 v87, v87
	v_exp_f32_e32 v88, v88
	v_exp_f32_e32 v89, v89
	v_exp_f32_e32 v90, v90
	s_waitcnt lgkmcnt(5)
	v_mfma_f32_32x32x16_bf16 v[34:49], v[216:219], v[70:73], v[34:49]
	ds_read_b128 v[240:243], v252 offset:39488
	v_exp_f32_e32 v91, v91
	v_exp_f32_e32 v92, v92
	v_exp_f32_e32 v93, v93
	v_exp_f32_e32 v94, v94
	v_exp_f32_e32 v95, v95
	s_waitcnt lgkmcnt(5)
	v_mfma_f32_32x32x16_bf16 v[18:33], v[220:223], v[70:73], v[18:33]
	ds_read_b128 v[196:199], v252 offset:25696
	v_exp_f32_e32 v96, v96
	v_exp_f32_e32 v97, v97
	v_cvt_pk_bf16_f32 v74, v82, v83
	v_cvt_pk_bf16_f32 v75, v84, v85
	v_cvt_pk_bf16_f32 v76, v86, v87
	s_waitcnt lgkmcnt(5)
	v_mfma_f32_32x32x16_bf16 v[2:17], v[224:227], v[70:73], v[2:17]
	ds_read_b128 v[200:203], v252 offset:30304
	v_cvt_pk_bf16_f32 v77, v88, v89
	s_waitcnt lgkmcnt(5)
	v_mfma_f32_32x32x16_bf16 v[50:65], v[228:231], v[74:77], v[50:65]
	ds_read_b128 v[204:207], v252 offset:34912
	v_cvt_pk_bf16_f32 v78, v90, v91
	v_cvt_pk_bf16_f32 v79, v92, v93
	v_cvt_pk_bf16_f32 v80, v94, v95
	v_cvt_pk_bf16_f32 v81, v96, v97
	s_waitcnt lgkmcnt(5)
	v_mfma_f32_32x32x16_bf16 v[34:49], v[232:235], v[74:77], v[34:49]
	ds_read_b128 v[208:211], v252 offset:39520
	v_pk_add_f32 v[184:185], v[184:185], v[82:83]
	v_pk_add_f32 v[186:187], v[186:187], v[84:85]
	v_pk_add_f32 v[184:185], v[184:185], v[86:87]
	v_pk_add_f32 v[186:187], v[186:187], v[88:89]
	s_waitcnt lgkmcnt(5)
	v_mfma_f32_32x32x16_bf16 v[18:33], v[236:239], v[74:77], v[18:33]
	v_pk_add_f32 v[184:185], v[184:185], v[90:91]
	v_pk_add_f32 v[186:187], v[186:187], v[92:93]
	v_pk_add_f32 v[184:185], v[184:185], v[94:95]
	v_pk_add_f32 v[186:187], v[186:187], v[96:97]
	s_waitcnt lgkmcnt(4)
	v_mfma_f32_32x32x16_bf16 v[2:17], v[240:243], v[74:77], v[2:17]
	v_pk_add_f32 v[184:185], v[184:185], v[186:187]
	v_add_f32_e32 v184, v184, v185
	v_add_f32_e32 v182, v182, v184
	s_waitcnt lgkmcnt(3)
	v_mfma_f32_32x32x16_bf16 v[50:65], v[196:199], v[78:81], v[50:65]
	s_bitcmp1_b32 s36, 0
	s_cselect_b32 s99, 0xac00, 0
	s_add_i32 s99, s99, 0
	v_add_u32_e32 v250, s99, v170
	s_waitcnt lgkmcnt(2)
	v_mfma_f32_32x32x16_bf16 v[34:49], v[200:203], v[78:81], v[34:49]
	s_waitcnt vmcnt(4)
	ds_write_b128 v250, v[98:101]
	s_waitcnt vmcnt(3)
	ds_write_b128 v250, v[102:105] offset:12800
	s_waitcnt lgkmcnt(3)
	v_mfma_f32_32x32x16_bf16 v[18:33], v[204:207], v[78:81], v[18:33]
	v_add_u32_e32 v250, s99, v172
	s_waitcnt vmcnt(2)
	ds_write_b128 v250, v[106:109] offset:256
	v_add_u32_e32 v250, s99, v169
	s_waitcnt lgkmcnt(3)
	v_mfma_f32_32x32x16_bf16 v[2:17], v[208:211], v[78:81], v[2:17]
	s_waitcnt vmcnt(1)
	ds_write_b128 v250, v[126:129] offset:25600
	s_waitcnt vmcnt(0)
	ds_write_b128 v250, v[150:153] offset:34816
	s_setprio 0
	s_branch .LBB0_1490
